# RET step after barrier 2: Q/K LDS-DMA block rewritten as SALU base stepping + SGPR-base DMA (no VALU address temps) and moved behind the 14 batched LDS reads so their latency overlaps DMA issue
# speedup vs baseline: 1.0064x; 1.0064x over previous
; #define LAS __attribute__((address_space(3)))
; DI unsigned pk2(float lo, float hi) { const f32x2 v = {lo, hi}; const hbf16x2 b = __builtin_convertvector(v, hbf16x2); return __builtin_bit_cast(unsigned, b); }
; #define LDS_BARRIER() do { asm volatile("s_waitcnt lgkmcnt(0)" ::: "memory"); __builtin_amdgcn_s_barrier(); } while (0)
; #define MFMA16(a, b, c) __builtin_amdgcn_mfma_f32_16x16x32_bf16((a), (b), (c), 0, 0, 0)
; DI void ret_chain_phase(const Ctx& a, LAS unsigned char* lds) {
;     ...
;             LDS_BARRIER();
;             if (s + 1 < 68) RC_DMA_QK(s + 1);
; #pragma unroll
;             for (int vv = 0; vv < 2; ++vv) {
;                 const int vt = 2 * half + vv;
; #pragma unroll
;                 for (int k2 = 0; k2 < 2; ++k2) {
;                     const bf16x8 vf = *(const LAS bf16x8*)(lds + A128(RC_SVT, vt, k2));
;                     const bf16x8 pf = *(const LAS bf16x8*)(lds + A128(RC_SP, it, k2));
;                     accO[vv] = MFMA16(vf, pf, accO[vv]);
;                 }
;                 u32x2 w; w.x = pk2(accO[vv][0], accO[vv][1]); w.y = pk2(accO[vv][2], accO[vv][3]);
;                 *(u32x2*)(O + (size_t)(row0 + icol) * 2048 + h * 512 + vs * 64 + 16 * vt + 4 * fq) = w;
;             }
;             bf16x8 vfr[4][2];
; #pragma unroll
;             for (int vt = 0; vt < 4; ++vt) { vfr[vt][0] = *(const LAS bf16x8*)(lds + A128(RC_SVT, vt, 0)); vfr[vt][1] = *(const LAS bf16x8*)(lds + A128(RC_SVT, vt, 1)); }
; #pragma unroll
;             for (int di = 0; di < 2; ++di) {
;                 const int dt = 2 * wid + di;
;                 bf16x8 kt[2];
; #pragma unroll
;                 for (int k2 = 0; k2 < 2; ++k2) kt[k2] = *(const LAS bf16x8*)(lds + A128(RC_SKT, dt, k2));
; #pragma unroll
;                 for (int vt = 0; vt < 4; ++vt) {
;                     f32x4 sacc = accS[di][vt] * cdec;
.LBB0_211:
	s_lshl_b32 s20, s30, 6
	s_add_i32 s20, s20, s31
	s_ashr_i32 s21, s20, 31
	s_lshl_b64 s[20:21], s[20:21], 11
	s_add_u32 s98, s76, s20
	s_addc_u32 s99, s77, s21
	s_add_u32 s20, s80, s20
	s_addc_u32 s21, s81, s21
	v_readfirstlane_b32 s100, v172
	v_lshrrev_b32_e32 v68, 1, v105
	v_add_u32_e32 v60, s50, v122
	v_ashrrev_i32_e32 v61, 31, v60
	v_lshlrev_b64 v[60:61], 12, v[60:61]
	v_lshl_add_u64 v[198:199], v[108:109], 0, v[60:61]
	v_lshlrev_b32_e32 v208, 7, v105
	v_bitop3_b32 v60, v68, v121, 7 bitop3:0x6c
	v_lshlrev_b32_e32 v209, 4, v60
	v_bitop3_b32 v60, v68, v129, 7 bitop3:0x6c
	v_lshlrev_b32_e32 v219, 4, v60
	v_pk_mul_f32 v[58:59], v[112:113], v[86:87]
	v_pk_mul_f32 v[56:57], v[110:111], v[84:85]
	v_pk_mul_f32 v[54:55], v[112:113], v[54:55]
	v_pk_mul_f32 v[52:53], v[110:111], v[52:53]
	v_add3_u32 v250, v128, v208, v209
	ds_read_b128 v[64:67], v250
	v_add3_u32 v250, v128, v208, v219
	ds_read_b128 v[68:71], v250
	v_add3_u32 v250, s2, v208, v209
	ds_read_b128 v[60:63], v250
	v_add3_u32 v250, s2, v208, v219
	ds_read_b128 v[72:75], v250
	v_add3_u32 v250, s84, v208, v209
	ds_read_b128 v[76:79], v250
	v_add3_u32 v250, s84, v208, v219
	ds_read_b128 v[80:83], v250
	v_add3_u32 v250, s85, v208, v209
	ds_read_b128 v[230:233], v250
	v_add3_u32 v250, s85, v208, v219
	ds_read_b128 v[234:237], v250
	v_add3_u32 v250, s24, v208, v209
	ds_read_b128 v[238:241], v250
	v_add3_u32 v250, s24, v208, v219
	ds_read_b128 v[242:245], v250
	v_add3_u32 v250, v168, v208, v209
	ds_read_b128 v[246:249], v250
	v_add3_u32 v250, v168, v208, v219
	ds_read_b128 v[194:197], v250
	v_add3_u32 v250, v169, v208, v209
	ds_read_b128 v[222:225], v250
	v_add3_u32 v250, v169, v208, v219
	ds_read_b128 v[84:87], v250
	s_add_i32 m0, s100, 0x0
	s_nop 0
	global_load_lds_dwordx4 v116, s[98:99]
	s_add_i32 m0, s100, 0x8000
	s_nop 0
	global_load_lds_dwordx4 v116, s[20:21]
	s_add_u32 s98, s98, 0x8000
	s_addc_u32 s99, s99, 0
	s_add_i32 m0, s100, 0x2000
	s_nop 0
	global_load_lds_dwordx4 v116, s[98:99]
	s_add_u32 s20, s20, 0x8000
	s_addc_u32 s21, s21, 0
	s_add_i32 m0, s100, 0xa000
	s_nop 0
	global_load_lds_dwordx4 v116, s[20:21]
	s_add_u32 s98, s98, 0x8000
	s_addc_u32 s99, s99, 0
	s_add_i32 m0, s100, 0x4000
	s_nop 0
	global_load_lds_dwordx4 v116, s[98:99]
	s_add_u32 s20, s20, 0x8000
	s_addc_u32 s21, s21, 0
	s_add_i32 m0, s100, 0xc000
	s_nop 0
	global_load_lds_dwordx4 v116, s[20:21]
	s_add_u32 s98, s98, 0x8000
	s_addc_u32 s99, s99, 0
	s_add_i32 m0, s100, 0x6000
	s_nop 0
	global_load_lds_dwordx4 v116, s[98:99]
	s_add_u32 s20, s20, 0x8000
	s_addc_u32 s21, s21, 0
	s_add_i32 m0, s100, 0xe000
	s_nop 0
	global_load_lds_dwordx4 v116, s[20:21]
	v_mov_b32_e32 v105, v104
	v_readfirstlane_b32 s20, v200
	v_pk_mul_f32 v[0:1], v[104:105], v[0:1]
	v_pk_mul_f32 v[2:3], v[104:105], v[2:3]
	v_pk_mul_f32 v[4:5], v[104:105], v[4:5]
	v_pk_mul_f32 v[6:7], v[104:105], v[6:7]
	v_pk_mul_f32 v[8:9], v[104:105], v[8:9]
	v_pk_mul_f32 v[10:11], v[104:105], v[10:11]
	v_pk_mul_f32 v[12:13], v[104:105], v[12:13]
	v_pk_mul_f32 v[14:15], v[104:105], v[14:15]
	v_pk_mul_f32 v[16:17], v[104:105], v[16:17]
	v_pk_mul_f32 v[18:19], v[104:105], v[18:19]
	v_pk_mul_f32 v[20:21], v[104:105], v[20:21]
	v_pk_mul_f32 v[22:23], v[104:105], v[22:23]
	v_pk_mul_f32 v[24:25], v[104:105], v[24:25]
	v_pk_mul_f32 v[26:27], v[104:105], v[26:27]
	v_pk_mul_f32 v[28:29], v[104:105], v[28:29]
	v_pk_mul_f32 v[30:31], v[104:105], v[30:31]
	s_cmp_lt_u32 s20, 0x100
	s_cbranch_scc0 .Lrc_h1
	s_waitcnt lgkmcnt(8)
	v_mfma_f32_16x16x32_bf16 v[56:59], v[60:63], v[64:67], v[56:59]
	v_mfma_f32_16x16x32_bf16 v[56:59], v[72:75], v[68:71], v[56:59]
	v_mfma_f32_16x16x32_bf16 v[52:55], v[76:79], v[64:67], v[52:55]
	v_mfma_f32_16x16x32_bf16 v[52:55], v[80:83], v[68:71], v[52:55]
	s_branch .Lrc_hj
